# P4 SwiGLU epilogue: 42 instead of 52 VALU per 8-output group (row scale folded into the packed exp argument, packed 1+e, gate*up before one packed multiply by sigmoid*scale^2; f32 re-association only)
# baseline (speedup 1.0000x reference)
; DI unsigned cvtpk(float lo, float hi) { f32x2_t v = {lo, hi}; bf16x2_t b = __builtin_convertvector(v, bf16x2_t); return __builtin_bit_cast(unsigned, b); }
; DI float silu_f(float x) { return x * __builtin_amdgcn_rcpf(1.0f + __expf(-x)); }
;     DI void operator()(const f32x4 (&acc)[2][2][4][2], const Unit& u, int wr, int wc, int fr, int fq) const {
;     ...
;         for (int ai = 0; ai < 2; ++ai)
; #pragma unroll
;             for (int m = 0; m < 4; ++m) {
;                 const int row = u.pm * 256 + 128 * ai + 64 * wr + 16 * m + fr;
;                 const float* sp = SSQ + (size_t)row * 16;
;                 const f32x4 s0 = *(const f32x4*)sp, s1 = *(const f32x4*)(sp + 4), s2 = *(const f32x4*)(sp + 8), s3 = *(const f32x4*)(sp + 12);
;                 float ss = 0.f;
; #pragma unroll
;                 for (int i = 0; i < 4; ++i) ss += s0[i] + s1[i] + s2[i] + s3[i];
;                 const float rs = rsqrtf(ss * (1.0f / DM) + EPS);
;                 float a[8];
; #pragma unroll
;                 for (int n = 0; n < 2; ++n)
; #pragma unroll
;                     for (int t = 0; t < 4; ++t) a[4 * n + t] = silu_f(acc[ai][0][m][n][t] * rs) * (acc[ai][1][m][n][t] * rs);
;                 u32x4 w; w.x = cvtpk(a[0], a[1]); w.y = cvtpk(a[2], a[3]); w.z = cvtpk(a[4], a[5]); w.w = cvtpk(a[6], a[7]);
;                 __builtin_nontemporal_store(w, (u32x4*)(ACT + (size_t)row * DFF + u.pn * 128 + 32 * wc + 8 * fq));
.LBB0_863:
	v_mov_b32_e32 v216, 1.0
	v_lshl_add_u32 v148, s24, 8, v150
	v_ashrrev_i32_e32 v149, 31, v148
	v_lshlrev_b64 v[146:147], 6, v[148:149]
	v_pk_add_f32 v[186:187], v[230:231], v[234:235]
	v_pk_add_f32 v[188:189], v[232:233], v[236:237]
	v_pk_add_f32 v[186:187], v[238:239], v[186:187]
	v_pk_add_f32 v[188:189], v[240:241], v[188:189]
	v_pk_add_f32 v[186:187], v[242:243], v[186:187]
	v_pk_add_f32 v[188:189], v[244:245], v[188:189]
	v_add_f32_e32 v190, 0, v186
	v_add_f32_e32 v190, v187, v190
	v_add_f32_e32 v190, v188, v190
	v_add_f32_e32 v190, v189, v190
	v_fmamk_f32 v190, v190, 0x3a800000, v155
	v_mul_f32_e32 v191, 0x4b800000, v190
	v_cmp_gt_f32_e32 vcc, s47, v190
	s_nop 1
	v_cndmask_b32_e32 v190, v190, v191, vcc
	v_rsq_f32_e32 v190, v190
	s_nop 1
	v_mul_f32_e32 v191, 0x45800000, v190
	v_cndmask_b32_e32 v190, v190, v191, vcc
	ds_write_b32 v247, v190
	s_waitcnt lgkmcnt(0)
	s_barrier
	v_mov_b32_e32 v202, 0x20000
	v_lshl_add_u32 v202, v150, 2, v202
	ds_read_b32 v186, v202 offset:0
	ds_read_b32 v188, v202 offset:64
	ds_read_b32 v190, v202 offset:128
	ds_read_b32 v192, v202 offset:192
	ds_read_b32 v194, v202 offset:512
	ds_read_b32 v196, v202 offset:576
	ds_read_b32 v198, v202 offset:640
	ds_read_b32 v200, v202 offset:704
	s_lshl_b32 s24, s25, 7
	v_mov_b64_e32 v[146:147], s[52:53]
	s_ashr_i32 s25, s24, 31
	v_mad_i64_i32 v[172:173], s[26:27], v148, s48, v[146:147]
	s_lshl_b64 s[24:25], s[24:25], 1
	v_lshl_add_u64 v[172:173], v[172:173], 0, s[24:25]
	v_or_b32_e32 v174, 16, v148
	v_ashrrev_i32_e32 v175, 31, v174
	v_lshlrev_b64 v[176:177], 6, v[174:175]
	v_lshl_add_u64 v[156:157], v[172:173], 0, s[8:9]
	v_lshl_add_u64 v[156:157], v[156:157], 0, v[136:137]
	s_waitcnt lgkmcnt(7)
	v_mul_f32_e32 v204, 0xbfb8aa3b, v186
	v_mul_f32_e32 v206, v186, v186
	v_pk_mul_f32 v[208:209], v[124:125], v[204:205] op_sel_hi:[1,0]
	v_pk_mul_f32 v[210:211], v[126:127], v[204:205] op_sel_hi:[1,0]
	v_pk_mul_f32 v[212:213], v[120:121], v[204:205] op_sel_hi:[1,0]
	v_pk_mul_f32 v[214:215], v[122:123], v[204:205] op_sel_hi:[1,0]
	v_exp_f32_e32 v208, v208
	v_exp_f32_e32 v209, v209
	v_exp_f32_e32 v210, v210
	v_exp_f32_e32 v211, v211
	v_exp_f32_e32 v212, v212
	v_exp_f32_e32 v213, v213
	v_exp_f32_e32 v214, v214
	v_exp_f32_e32 v215, v215
	v_pk_add_f32 v[208:209], v[208:209], v[216:217] op_sel_hi:[1,0]
	v_pk_add_f32 v[210:211], v[210:211], v[216:217] op_sel_hi:[1,0]
	v_pk_add_f32 v[212:213], v[212:213], v[216:217] op_sel_hi:[1,0]
	v_pk_add_f32 v[214:215], v[214:215], v[216:217] op_sel_hi:[1,0]
	v_rcp_f32_e32 v208, v208
	v_rcp_f32_e32 v209, v209
	v_rcp_f32_e32 v210, v210
	v_rcp_f32_e32 v211, v211
	v_rcp_f32_e32 v212, v212
	v_rcp_f32_e32 v213, v213
	v_rcp_f32_e32 v214, v214
	v_rcp_f32_e32 v215, v215
	v_pk_mul_f32 v[208:209], v[208:209], v[206:207] op_sel_hi:[1,0]
	v_pk_mul_f32 v[210:211], v[210:211], v[206:207] op_sel_hi:[1,0]
	v_pk_mul_f32 v[212:213], v[212:213], v[206:207] op_sel_hi:[1,0]
	v_pk_mul_f32 v[214:215], v[214:215], v[206:207] op_sel_hi:[1,0]
	v_pk_mul_f32 v[116:117], v[116:117], v[124:125]
	v_pk_mul_f32 v[118:119], v[118:119], v[126:127]
	v_pk_mul_f32 v[120:121], v[112:113], v[120:121]
	v_pk_mul_f32 v[122:123], v[114:115], v[122:123]
	v_pk_mul_f32 v[116:117], v[116:117], v[208:209]
	v_pk_mul_f32 v[118:119], v[118:119], v[210:211]
	v_pk_mul_f32 v[120:121], v[120:121], v[212:213]
	v_pk_mul_f32 v[122:123], v[122:123], v[214:215]
	v_cvt_pk_bf16_f32 v112, v116, v117
	v_cvt_pk_bf16_f32 v113, v118, v119
	v_cvt_pk_bf16_f32 v114, v120, v121
	v_cvt_pk_bf16_f32 v115, v122, v123
	global_store_dwordx4 v[156:157], v[112:115], off nt
	v_mad_i64_i32 v[158:159], s[26:27], v174, s48, v[146:147]
	v_or_b32_e32 v156, 32, v148
	v_lshl_add_u64 v[158:159], v[158:159], 0, s[24:25]
	v_ashrrev_i32_e32 v157, 31, v156
	v_lshlrev_b64 v[160:161], 6, v[156:157]
	v_lshl_add_u64 v[112:113], v[158:159], 0, s[8:9]
	v_lshl_add_u64 v[112:113], v[112:113], 0, v[136:137]
	s_waitcnt lgkmcnt(6)
	v_mul_f32_e32 v204, 0xbfb8aa3b, v188
	v_mul_f32_e32 v206, v188, v188
	v_pk_mul_f32 v[208:209], v[108:109], v[204:205] op_sel_hi:[1,0]
	v_pk_mul_f32 v[210:211], v[110:111], v[204:205] op_sel_hi:[1,0]
	v_pk_mul_f32 v[212:213], v[104:105], v[204:205] op_sel_hi:[1,0]
	v_pk_mul_f32 v[214:215], v[106:107], v[204:205] op_sel_hi:[1,0]
	v_exp_f32_e32 v208, v208
	v_exp_f32_e32 v209, v209
	v_exp_f32_e32 v210, v210
	v_exp_f32_e32 v211, v211
	v_exp_f32_e32 v212, v212
	v_exp_f32_e32 v213, v213
	v_exp_f32_e32 v214, v214
	v_exp_f32_e32 v215, v215
	v_pk_add_f32 v[208:209], v[208:209], v[216:217] op_sel_hi:[1,0]
	v_pk_add_f32 v[210:211], v[210:211], v[216:217] op_sel_hi:[1,0]
	v_pk_add_f32 v[212:213], v[212:213], v[216:217] op_sel_hi:[1,0]
	v_pk_add_f32 v[214:215], v[214:215], v[216:217] op_sel_hi:[1,0]
	v_rcp_f32_e32 v208, v208
	v_rcp_f32_e32 v209, v209
	v_rcp_f32_e32 v210, v210
	v_rcp_f32_e32 v211, v211
	v_rcp_f32_e32 v212, v212
	v_rcp_f32_e32 v213, v213
	v_rcp_f32_e32 v214, v214
	v_rcp_f32_e32 v215, v215
	v_pk_mul_f32 v[208:209], v[208:209], v[206:207] op_sel_hi:[1,0]
	v_pk_mul_f32 v[210:211], v[210:211], v[206:207] op_sel_hi:[1,0]
	v_pk_mul_f32 v[212:213], v[212:213], v[206:207] op_sel_hi:[1,0]
	v_pk_mul_f32 v[214:215], v[214:215], v[206:207] op_sel_hi:[1,0]
	v_pk_mul_f32 v[100:101], v[100:101], v[108:109]
	v_pk_mul_f32 v[102:103], v[102:103], v[110:111]
	v_pk_mul_f32 v[104:105], v[96:97], v[104:105]
	v_pk_mul_f32 v[106:107], v[98:99], v[106:107]
	v_pk_mul_f32 v[100:101], v[100:101], v[208:209]
	v_pk_mul_f32 v[102:103], v[102:103], v[210:211]
	v_pk_mul_f32 v[104:105], v[104:105], v[212:213]
	v_pk_mul_f32 v[106:107], v[106:107], v[214:215]
	v_cvt_pk_bf16_f32 v96, v100, v101
	v_cvt_pk_bf16_f32 v97, v102, v103
	v_cvt_pk_bf16_f32 v98, v104, v105
	v_cvt_pk_bf16_f32 v99, v106, v107
	global_store_dwordx4 v[112:113], v[96:99], off nt
	v_mad_i64_i32 v[114:115], s[26:27], v156, s48, v[146:147]
	v_or_b32_e32 v112, 48, v148
	v_lshl_add_u64 v[114:115], v[114:115], 0, s[24:25]
	v_ashrrev_i32_e32 v113, 31, v112
	v_lshlrev_b64 v[116:117], 6, v[112:113]
	v_lshl_add_u64 v[96:97], v[114:115], 0, s[8:9]
	v_lshl_add_u64 v[96:97], v[96:97], 0, v[136:137]
	s_waitcnt lgkmcnt(5)
; DI unsigned cvtpk(float lo, float hi) { f32x2_t v = {lo, hi}; bf16x2_t b = __builtin_convertvector(v, bf16x2_t); return __builtin_bit_cast(unsigned, b); }
; DI float silu_f(float x) { return x * __builtin_amdgcn_rcpf(1.0f + __expf(-x)); }
;     DI void operator()(const f32x4 (&acc)[2][2][4][2], const Unit& u, int wr, int wc, int fr, int fq) const {
;     ...
;                 const float* sp = SSQ + (size_t)row * 16;
;                 const f32x4 s0 = *(const f32x4*)sp, s1 = *(const f32x4*)(sp + 4), s2 = *(const f32x4*)(sp + 8), s3 = *(const f32x4*)(sp + 12);
;                 float ss = 0.f;
; #pragma unroll
;                 for (int i = 0; i < 4; ++i) ss += s0[i] + s1[i] + s2[i] + s3[i];
;                 const float rs = rsqrtf(ss * (1.0f / DM) + EPS);
;                 float a[8];
; #pragma unroll
;                 for (int n = 0; n < 2; ++n)
; #pragma unroll
;                     for (int t = 0; t < 4; ++t) a[4 * n + t] = silu_f(acc[ai][0][m][n][t] * rs) * (acc[ai][1][m][n][t] * rs);
;                 u32x4 w; w.x = cvtpk(a[0], a[1]); w.y = cvtpk(a[2], a[3]); w.z = cvtpk(a[4], a[5]); w.w = cvtpk(a[6], a[7]);
;                 __builtin_nontemporal_store(w, (u32x4*)(ACT + (size_t)row * DFF + u.pn * 128 + 32 * wc + 8 * fq));
	v_mul_f32_e32 v204, 0xbfb8aa3b, v190
	v_mul_f32_e32 v206, v190, v190
	v_pk_mul_f32 v[208:209], v[92:93], v[204:205] op_sel_hi:[1,0]
	v_pk_mul_f32 v[210:211], v[94:95], v[204:205] op_sel_hi:[1,0]
	v_pk_mul_f32 v[212:213], v[88:89], v[204:205] op_sel_hi:[1,0]
	v_pk_mul_f32 v[214:215], v[90:91], v[204:205] op_sel_hi:[1,0]
	v_exp_f32_e32 v208, v208
	v_exp_f32_e32 v209, v209
	v_exp_f32_e32 v210, v210
	v_exp_f32_e32 v211, v211
	v_exp_f32_e32 v212, v212
	v_exp_f32_e32 v213, v213
	v_exp_f32_e32 v214, v214
	v_exp_f32_e32 v215, v215
	v_pk_add_f32 v[208:209], v[208:209], v[216:217] op_sel_hi:[1,0]
	v_pk_add_f32 v[210:211], v[210:211], v[216:217] op_sel_hi:[1,0]
	v_pk_add_f32 v[212:213], v[212:213], v[216:217] op_sel_hi:[1,0]
	v_pk_add_f32 v[214:215], v[214:215], v[216:217] op_sel_hi:[1,0]
	v_rcp_f32_e32 v208, v208
	v_rcp_f32_e32 v209, v209
	v_rcp_f32_e32 v210, v210
	v_rcp_f32_e32 v211, v211
	v_rcp_f32_e32 v212, v212
	v_rcp_f32_e32 v213, v213
	v_rcp_f32_e32 v214, v214
	v_rcp_f32_e32 v215, v215
	v_pk_mul_f32 v[208:209], v[208:209], v[206:207] op_sel_hi:[1,0]
	v_pk_mul_f32 v[210:211], v[210:211], v[206:207] op_sel_hi:[1,0]
	v_pk_mul_f32 v[212:213], v[212:213], v[206:207] op_sel_hi:[1,0]
	v_pk_mul_f32 v[214:215], v[214:215], v[206:207] op_sel_hi:[1,0]
	v_pk_mul_f32 v[84:85], v[84:85], v[92:93]
	v_pk_mul_f32 v[86:87], v[86:87], v[94:95]
	v_pk_mul_f32 v[88:89], v[80:81], v[88:89]
	v_pk_mul_f32 v[90:91], v[82:83], v[90:91]
	v_pk_mul_f32 v[84:85], v[84:85], v[208:209]
	v_pk_mul_f32 v[86:87], v[86:87], v[210:211]
	v_pk_mul_f32 v[88:89], v[88:89], v[212:213]
	v_pk_mul_f32 v[90:91], v[90:91], v[214:215]
	v_cvt_pk_bf16_f32 v80, v84, v85
	v_cvt_pk_bf16_f32 v81, v86, v87
	v_cvt_pk_bf16_f32 v82, v88, v89
	v_cvt_pk_bf16_f32 v83, v90, v91
	global_store_dwordx4 v[96:97], v[80:83], off nt
	v_mad_i64_i32 v[98:99], s[26:27], v112, s48, v[146:147]
	v_add_u32_e32 v96, 0x80, v148
	v_lshl_add_u64 v[98:99], v[98:99], 0, s[24:25]
	v_ashrrev_i32_e32 v97, 31, v96
	v_lshlrev_b64 v[100:101], 6, v[96:97]
	v_lshl_add_u64 v[80:81], v[98:99], 0, s[8:9]
	v_lshl_add_u64 v[80:81], v[80:81], 0, v[136:137]
	s_waitcnt lgkmcnt(4)
	v_mul_f32_e32 v204, 0xbfb8aa3b, v192
	v_mul_f32_e32 v206, v192, v192
	v_pk_mul_f32 v[208:209], v[76:77], v[204:205] op_sel_hi:[1,0]
	v_pk_mul_f32 v[210:211], v[78:79], v[204:205] op_sel_hi:[1,0]
	v_pk_mul_f32 v[212:213], v[72:73], v[204:205] op_sel_hi:[1,0]
	v_pk_mul_f32 v[214:215], v[74:75], v[204:205] op_sel_hi:[1,0]
	v_exp_f32_e32 v208, v208
	v_exp_f32_e32 v209, v209
	v_exp_f32_e32 v210, v210
	v_exp_f32_e32 v211, v211
	v_exp_f32_e32 v212, v212
	v_exp_f32_e32 v213, v213
	v_exp_f32_e32 v214, v214
	v_exp_f32_e32 v215, v215
	v_pk_add_f32 v[208:209], v[208:209], v[216:217] op_sel_hi:[1,0]
	v_pk_add_f32 v[210:211], v[210:211], v[216:217] op_sel_hi:[1,0]
	v_pk_add_f32 v[212:213], v[212:213], v[216:217] op_sel_hi:[1,0]
	v_pk_add_f32 v[214:215], v[214:215], v[216:217] op_sel_hi:[1,0]
	v_rcp_f32_e32 v208, v208
	v_rcp_f32_e32 v209, v209
	v_rcp_f32_e32 v210, v210
	v_rcp_f32_e32 v211, v211
	v_rcp_f32_e32 v212, v212
	v_rcp_f32_e32 v213, v213
	v_rcp_f32_e32 v214, v214
	v_rcp_f32_e32 v215, v215
	v_pk_mul_f32 v[208:209], v[208:209], v[206:207] op_sel_hi:[1,0]
	v_pk_mul_f32 v[210:211], v[210:211], v[206:207] op_sel_hi:[1,0]
	v_pk_mul_f32 v[212:213], v[212:213], v[206:207] op_sel_hi:[1,0]
	v_pk_mul_f32 v[214:215], v[214:215], v[206:207] op_sel_hi:[1,0]
	v_pk_mul_f32 v[68:69], v[68:69], v[76:77]
	v_pk_mul_f32 v[70:71], v[70:71], v[78:79]
	v_pk_mul_f32 v[72:73], v[64:65], v[72:73]
	v_pk_mul_f32 v[74:75], v[66:67], v[74:75]
	v_pk_mul_f32 v[68:69], v[68:69], v[208:209]
	v_pk_mul_f32 v[70:71], v[70:71], v[210:211]
	v_pk_mul_f32 v[72:73], v[72:73], v[212:213]
	v_pk_mul_f32 v[74:75], v[74:75], v[214:215]
	v_cvt_pk_bf16_f32 v64, v68, v69
	v_cvt_pk_bf16_f32 v65, v70, v71
	v_cvt_pk_bf16_f32 v66, v72, v73
	v_cvt_pk_bf16_f32 v67, v74, v75
	global_store_dwordx4 v[80:81], v[64:67], off nt
	v_mad_i64_i32 v[82:83], s[26:27], v96, s48, v[146:147]
	v_add_u32_e32 v80, 0x90, v148
	v_lshl_add_u64 v[82:83], v[82:83], 0, s[24:25]
	v_ashrrev_i32_e32 v81, 31, v80
	v_lshlrev_b64 v[84:85], 6, v[80:81]
	v_lshl_add_u64 v[64:65], v[82:83], 0, s[8:9]
	v_lshl_add_u64 v[64:65], v[64:65], 0, v[136:137]
	s_waitcnt lgkmcnt(3)
	v_mul_f32_e32 v204, 0xbfb8aa3b, v194
	v_mul_f32_e32 v206, v194, v194
	v_pk_mul_f32 v[208:209], v[60:61], v[204:205] op_sel_hi:[1,0]
	v_pk_mul_f32 v[210:211], v[62:63], v[204:205] op_sel_hi:[1,0]
	v_pk_mul_f32 v[212:213], v[56:57], v[204:205] op_sel_hi:[1,0]
	v_pk_mul_f32 v[214:215], v[58:59], v[204:205] op_sel_hi:[1,0]
	v_exp_f32_e32 v208, v208
	v_exp_f32_e32 v209, v209
	v_exp_f32_e32 v210, v210
	v_exp_f32_e32 v211, v211
	v_exp_f32_e32 v212, v212
	v_exp_f32_e32 v213, v213
	v_exp_f32_e32 v214, v214
	v_exp_f32_e32 v215, v215
	v_pk_add_f32 v[208:209], v[208:209], v[216:217] op_sel_hi:[1,0]
	v_pk_add_f32 v[210:211], v[210:211], v[216:217] op_sel_hi:[1,0]
	v_pk_add_f32 v[212:213], v[212:213], v[216:217] op_sel_hi:[1,0]
	v_pk_add_f32 v[214:215], v[214:215], v[216:217] op_sel_hi:[1,0]
	v_rcp_f32_e32 v208, v208
	v_rcp_f32_e32 v209, v209
	v_rcp_f32_e32 v210, v210
	v_rcp_f32_e32 v211, v211
	v_rcp_f32_e32 v212, v212
	v_rcp_f32_e32 v213, v213
	v_rcp_f32_e32 v214, v214
	v_rcp_f32_e32 v215, v215
	v_pk_mul_f32 v[208:209], v[208:209], v[206:207] op_sel_hi:[1,0]
	v_pk_mul_f32 v[210:211], v[210:211], v[206:207] op_sel_hi:[1,0]
	v_pk_mul_f32 v[212:213], v[212:213], v[206:207] op_sel_hi:[1,0]
	v_pk_mul_f32 v[214:215], v[214:215], v[206:207] op_sel_hi:[1,0]
	v_pk_mul_f32 v[52:53], v[52:53], v[60:61]
	v_pk_mul_f32 v[54:55], v[54:55], v[62:63]
	v_pk_mul_f32 v[56:57], v[48:49], v[56:57]
	v_pk_mul_f32 v[58:59], v[50:51], v[58:59]
	v_pk_mul_f32 v[52:53], v[52:53], v[208:209]
	v_pk_mul_f32 v[54:55], v[54:55], v[210:211]
	v_pk_mul_f32 v[56:57], v[56:57], v[212:213]
	v_pk_mul_f32 v[58:59], v[58:59], v[214:215]
	v_cvt_pk_bf16_f32 v48, v52, v53
	v_cvt_pk_bf16_f32 v49, v54, v55
	v_cvt_pk_bf16_f32 v50, v56, v57
	v_cvt_pk_bf16_f32 v51, v58, v59
	global_store_dwordx4 v[64:65], v[48:51], off nt
	v_mad_i64_i32 v[66:67], s[26:27], v80, s48, v[146:147]
	v_add_u32_e32 v64, 0xa0, v148
	v_lshl_add_u64 v[66:67], v[66:67], 0, s[24:25]
	v_ashrrev_i32_e32 v65, 31, v64
	v_lshlrev_b64 v[68:69], 6, v[64:65]
	v_lshl_add_u64 v[48:49], v[66:67], 0, s[8:9]
	v_lshl_add_u64 v[48:49], v[48:49], 0, v[136:137]
	s_waitcnt lgkmcnt(2)
; #define PG8_BAR __builtin_amdgcn_s_barrier()
; DI unsigned cvtpk(float lo, float hi) { f32x2_t v = {lo, hi}; bf16x2_t b = __builtin_convertvector(v, bf16x2_t); return __builtin_bit_cast(unsigned, b); }
; DI float silu_f(float x) { return x * __builtin_amdgcn_rcpf(1.0f + __expf(-x)); }
; template <class Epi, class Sched, bool ALIGN_EPI = false, bool SP2 = false>
; __device__ __forceinline__ void gemm_phase(PG8_LAS unsigned char* lds, const Gemm g, const Sched& S, const Epi& E) {
;     ...
;         if (!has_next) break;
; #pragma unroll
;         for (int a = 0; a < 2; ++a)
; #pragma unroll
;             for (int b = 0; b < 2; ++b)
; #pragma unroll
;                 for (int m = 0; m < 4; ++m)
; #pragma unroll
;                     for (int n = 0; n < 2; ++n) acc[a][b][m][n] = (f32x4){0.f, 0.f, 0.f, 0.f};
;         cur = nxt; cA = nA; cB = nB; ++ui;
;         if constexpr (ALIGN_EPI) { if (wr == 1) PG8_BAR; }
;     DI void operator()(const f32x4 (&acc)[2][2][4][2], const Unit& u, int wr, int wc, int fr, int fq) const {
;     ...
;                 const float* sp = SSQ + (size_t)row * 16;
;                 const f32x4 s0 = *(const f32x4*)sp, s1 = *(const f32x4*)(sp + 4), s2 = *(const f32x4*)(sp + 8), s3 = *(const f32x4*)(sp + 12);
;                 float ss = 0.f;
; #pragma unroll
;                 for (int i = 0; i < 4; ++i) ss += s0[i] + s1[i] + s2[i] + s3[i];
;                 const float rs = rsqrtf(ss * (1.0f / DM) + EPS);
;                 float a[8];
; #pragma unroll
;                 for (int n = 0; n < 2; ++n)
; #pragma unroll
;                     for (int t = 0; t < 4; ++t) a[4 * n + t] = silu_f(acc[ai][0][m][n][t] * rs) * (acc[ai][1][m][n][t] * rs);
;                 u32x4 w; w.x = cvtpk(a[0], a[1]); w.y = cvtpk(a[2], a[3]); w.z = cvtpk(a[4], a[5]); w.w = cvtpk(a[6], a[7]);
;                 __builtin_nontemporal_store(w, (u32x4*)(ACT + (size_t)row * DFF + u.pn * 128 + 32 * wc + 8 * fq));
	v_mul_f32_e32 v204, 0xbfb8aa3b, v196
	v_mul_f32_e32 v206, v196, v196
	v_pk_mul_f32 v[208:209], v[44:45], v[204:205] op_sel_hi:[1,0]
	v_pk_mul_f32 v[210:211], v[46:47], v[204:205] op_sel_hi:[1,0]
	v_pk_mul_f32 v[212:213], v[40:41], v[204:205] op_sel_hi:[1,0]
	v_pk_mul_f32 v[214:215], v[42:43], v[204:205] op_sel_hi:[1,0]
	v_exp_f32_e32 v208, v208
	v_exp_f32_e32 v209, v209
	v_exp_f32_e32 v210, v210
	v_exp_f32_e32 v211, v211
	v_exp_f32_e32 v212, v212
	v_exp_f32_e32 v213, v213
	v_exp_f32_e32 v214, v214
	v_exp_f32_e32 v215, v215
	v_pk_add_f32 v[208:209], v[208:209], v[216:217] op_sel_hi:[1,0]
	v_pk_add_f32 v[210:211], v[210:211], v[216:217] op_sel_hi:[1,0]
	v_pk_add_f32 v[212:213], v[212:213], v[216:217] op_sel_hi:[1,0]
	v_pk_add_f32 v[214:215], v[214:215], v[216:217] op_sel_hi:[1,0]
	v_rcp_f32_e32 v208, v208
	v_rcp_f32_e32 v209, v209
	v_rcp_f32_e32 v210, v210
	v_rcp_f32_e32 v211, v211
	v_rcp_f32_e32 v212, v212
	v_rcp_f32_e32 v213, v213
	v_rcp_f32_e32 v214, v214
	v_rcp_f32_e32 v215, v215
	v_pk_mul_f32 v[208:209], v[208:209], v[206:207] op_sel_hi:[1,0]
	v_pk_mul_f32 v[210:211], v[210:211], v[206:207] op_sel_hi:[1,0]
	v_pk_mul_f32 v[212:213], v[212:213], v[206:207] op_sel_hi:[1,0]
	v_pk_mul_f32 v[214:215], v[214:215], v[206:207] op_sel_hi:[1,0]
	v_pk_mul_f32 v[36:37], v[36:37], v[44:45]
	v_pk_mul_f32 v[38:39], v[38:39], v[46:47]
	v_pk_mul_f32 v[40:41], v[32:33], v[40:41]
	v_pk_mul_f32 v[42:43], v[34:35], v[42:43]
	v_pk_mul_f32 v[36:37], v[36:37], v[208:209]
	v_pk_mul_f32 v[38:39], v[38:39], v[210:211]
	v_pk_mul_f32 v[40:41], v[40:41], v[212:213]
	v_pk_mul_f32 v[42:43], v[42:43], v[214:215]
	v_cvt_pk_bf16_f32 v32, v36, v37
	v_cvt_pk_bf16_f32 v33, v38, v39
	v_cvt_pk_bf16_f32 v34, v40, v41
	v_cvt_pk_bf16_f32 v35, v42, v43
	global_store_dwordx4 v[48:49], v[32:35], off nt
	v_mad_i64_i32 v[50:51], s[26:27], v64, s48, v[146:147]
	v_add_u32_e32 v48, 0xb0, v148
	v_lshl_add_u64 v[50:51], v[50:51], 0, s[24:25]
	v_ashrrev_i32_e32 v49, 31, v48
	v_lshlrev_b64 v[52:53], 6, v[48:49]
	v_lshl_add_u64 v[32:33], v[50:51], 0, s[8:9]
	v_lshl_add_u64 v[32:33], v[32:33], 0, v[136:137]
	s_waitcnt lgkmcnt(1)
	v_mul_f32_e32 v204, 0xbfb8aa3b, v198
	v_mul_f32_e32 v206, v198, v198
	v_pk_mul_f32 v[208:209], v[28:29], v[204:205] op_sel_hi:[1,0]
	v_pk_mul_f32 v[210:211], v[30:31], v[204:205] op_sel_hi:[1,0]
	v_pk_mul_f32 v[212:213], v[24:25], v[204:205] op_sel_hi:[1,0]
	v_pk_mul_f32 v[214:215], v[26:27], v[204:205] op_sel_hi:[1,0]
	v_exp_f32_e32 v208, v208
	v_exp_f32_e32 v209, v209
	v_exp_f32_e32 v210, v210
	v_exp_f32_e32 v211, v211
	v_exp_f32_e32 v212, v212
	v_exp_f32_e32 v213, v213
	v_exp_f32_e32 v214, v214
	v_exp_f32_e32 v215, v215
	v_pk_add_f32 v[208:209], v[208:209], v[216:217] op_sel_hi:[1,0]
	v_pk_add_f32 v[210:211], v[210:211], v[216:217] op_sel_hi:[1,0]
	v_pk_add_f32 v[212:213], v[212:213], v[216:217] op_sel_hi:[1,0]
	v_pk_add_f32 v[214:215], v[214:215], v[216:217] op_sel_hi:[1,0]
	v_rcp_f32_e32 v208, v208
	v_rcp_f32_e32 v209, v209
	v_rcp_f32_e32 v210, v210
	v_rcp_f32_e32 v211, v211
	v_rcp_f32_e32 v212, v212
	v_rcp_f32_e32 v213, v213
	v_rcp_f32_e32 v214, v214
	v_rcp_f32_e32 v215, v215
	v_pk_mul_f32 v[208:209], v[208:209], v[206:207] op_sel_hi:[1,0]
	v_pk_mul_f32 v[210:211], v[210:211], v[206:207] op_sel_hi:[1,0]
	v_pk_mul_f32 v[212:213], v[212:213], v[206:207] op_sel_hi:[1,0]
	v_pk_mul_f32 v[214:215], v[214:215], v[206:207] op_sel_hi:[1,0]
	v_pk_mul_f32 v[20:21], v[20:21], v[28:29]
	v_pk_mul_f32 v[22:23], v[22:23], v[30:31]
	v_pk_mul_f32 v[24:25], v[16:17], v[24:25]
	v_pk_mul_f32 v[26:27], v[18:19], v[26:27]
	v_pk_mul_f32 v[20:21], v[20:21], v[208:209]
	v_pk_mul_f32 v[22:23], v[22:23], v[210:211]
	v_pk_mul_f32 v[24:25], v[24:25], v[212:213]
	v_pk_mul_f32 v[26:27], v[26:27], v[214:215]
	v_cvt_pk_bf16_f32 v16, v20, v21
	v_cvt_pk_bf16_f32 v17, v22, v23
	v_cvt_pk_bf16_f32 v18, v24, v25
	v_cvt_pk_bf16_f32 v19, v26, v27
	global_store_dwordx4 v[32:33], v[16:19], off nt
	s_andn2_b64 vcc, exec, s[6:7]
	v_mad_i64_i32 v[32:33], s[26:27], v48, s48, v[146:147]
	v_lshl_add_u64 v[16:17], v[32:33], 0, s[24:25]
	v_lshl_add_u64 v[16:17], v[16:17], 0, s[8:9]
	v_lshl_add_u64 v[16:17], v[16:17], 0, v[136:137]
	s_waitcnt lgkmcnt(0)
	v_mul_f32_e32 v204, 0xbfb8aa3b, v200
	v_mul_f32_e32 v206, v200, v200
	v_pk_mul_f32 v[208:209], v[12:13], v[204:205] op_sel_hi:[1,0]
	v_pk_mul_f32 v[210:211], v[14:15], v[204:205] op_sel_hi:[1,0]
	v_pk_mul_f32 v[212:213], v[8:9], v[204:205] op_sel_hi:[1,0]
	v_pk_mul_f32 v[214:215], v[10:11], v[204:205] op_sel_hi:[1,0]
	v_exp_f32_e32 v208, v208
	v_exp_f32_e32 v209, v209
	v_exp_f32_e32 v210, v210
	v_exp_f32_e32 v211, v211
	v_exp_f32_e32 v212, v212
	v_exp_f32_e32 v213, v213
	v_exp_f32_e32 v214, v214
	v_exp_f32_e32 v215, v215
	v_pk_add_f32 v[208:209], v[208:209], v[216:217] op_sel_hi:[1,0]
	v_pk_add_f32 v[210:211], v[210:211], v[216:217] op_sel_hi:[1,0]
	v_pk_add_f32 v[212:213], v[212:213], v[216:217] op_sel_hi:[1,0]
	v_pk_add_f32 v[214:215], v[214:215], v[216:217] op_sel_hi:[1,0]
	v_rcp_f32_e32 v208, v208
	v_rcp_f32_e32 v209, v209
	v_rcp_f32_e32 v210, v210
	v_rcp_f32_e32 v211, v211
	v_rcp_f32_e32 v212, v212
	v_rcp_f32_e32 v213, v213
	v_rcp_f32_e32 v214, v214
	v_rcp_f32_e32 v215, v215
	v_pk_mul_f32 v[208:209], v[208:209], v[206:207] op_sel_hi:[1,0]
	v_pk_mul_f32 v[210:211], v[210:211], v[206:207] op_sel_hi:[1,0]
	v_pk_mul_f32 v[212:213], v[212:213], v[206:207] op_sel_hi:[1,0]
	v_pk_mul_f32 v[214:215], v[214:215], v[206:207] op_sel_hi:[1,0]
	v_pk_mul_f32 v[4:5], v[4:5], v[12:13]
	v_pk_mul_f32 v[6:7], v[6:7], v[14:15]
	v_pk_mul_f32 v[8:9], v[0:1], v[8:9]
	v_pk_mul_f32 v[10:11], v[2:3], v[10:11]
	v_pk_mul_f32 v[4:5], v[4:5], v[208:209]
	v_pk_mul_f32 v[6:7], v[6:7], v[210:211]
	v_pk_mul_f32 v[8:9], v[8:9], v[212:213]
	v_pk_mul_f32 v[10:11], v[10:11], v[214:215]
	v_cvt_pk_bf16_f32 v0, v4, v5
	v_cvt_pk_bf16_f32 v1, v6, v7
	v_cvt_pk_bf16_f32 v2, v8, v9
	v_cvt_pk_bf16_f32 v3, v10, v11
	s_mov_b64 s[6:7], -1
	global_store_dwordx4 v[16:17], v[0:3], off nt
	s_cbranch_vccnz .LBB0_856
	s_andn2_b64 vcc, exec, s[10:11]
	s_cbranch_vccnz .LBB0_855
	s_barrier
	s_branch .LBB0_855
